# out-proj residual GEMM phases: one-sleep start stagger for odd in-XCD blocks, on top of v74
# baseline (speedup 1.0000x reference)
.LBB0_156:
	s_load_dwordx4 s[16:19], s[0:1], 0xf8
	s_add_i32 s2, s13, -3
	s_ashr_i32 s28, s2, 3
	s_ashr_i32 s29, s28, 31
	s_and_b32 s90, s2, 7
	s_waitcnt lgkmcnt(0)
	s_mov_b64 s[4:5], s[16:17]
	s_lshl_b64 s[8:9], s[28:29], 26
	s_add_u32 s20, s4, s8
	s_addc_u32 s21, s5, s9
	s_add_u32 s96, s44, 0x170c0000
	s_addc_u32 s97, s45, 0
	s_add_u32 s34, s44, 0x1d500000
	s_addc_u32 s35, s45, 0
	s_add_u32 s4, s44, 0x3880000
	v_readlane_b32 s85, v255, 2
	v_writelane_b32 v255, s2, 22
	s_addc_u32 s5, s45, 0
	v_writelane_b32 v255, s4, 23
	s_cmp_lt_i32 s90, 4
	s_nop 0
	v_writelane_b32 v255, s5, 24
	s_mov_b64 s[4:5], -1
	s_cbranch_scc1 .LBB0_754
	s_cmp_lt_i32 s90, 6
	v_writelane_b32 v255, s90, 25
	s_cbranch_scc1 .LBB0_331
	s_cmp_gt_i32 s90, 6
	s_cbranch_scc0 .LBB0_191
	v_readlane_b32 s98, v255, 18
	s_bitcmp0_b32 s98, 3
	s_cbranch_scc1 .Lstag_skip_or
	s_sleep 0x7f
.Lstag_skip_or:
	s_mov_b32 s13, s46
	s_mov_b32 s29, s87
	s_waitcnt vmcnt(0)
	v_mov_b32_e32 v8, v228
	s_mov_b64 s[92:93], s[34:35]
	s_cmpk_gt_i32 s29, 0xff
	v_readfirstlane_b32 s35, v8
	s_cbranch_scc1 .LBB0_179
	s_ashr_i32 s37, s29, 31
	s_lshr_b32 s2, s37, 29
	s_add_i32 s9, s29, s2
	s_and_b32 s2, s9, -8
	s_sub_i32 s8, s29, s2
	s_cmp_gt_i32 s8, -1
	s_cbranch_scc0 .LBB0_162
	s_lshl_b32 s2, s8, 5
	s_mov_b64 s[4:5], 0
